# speedup vs baseline: 1.0029x; 1.0029x over previous
; __device__ __forceinline__ int ptid() { int t = __builtin_amdgcn_workitem_id_x(); asm volatile("" : "+v"(t)); return t; }
; __device__ __forceinline__ unsigned xb_xcc_id() { return (unsigned)__builtin_amdgcn_s_getreg((3 << 11) | 20) & 0xFu; }
; __device__ __forceinline__ unsigned xb_add(unsigned* p, unsigned v) { return __hip_atomic_fetch_add(p, v, __ATOMIC_RELAXED, __HIP_MEMORY_SCOPE_AGENT); }
;   if (ptid() == 0) {
;     const unsigned x = xb_xcc_id();
;     xb_add(&bar[XB_XCNT(x)], 1u);
; __global__ void __launch_bounds__(256, 2) mega(Params p) {
;   __shared__ __attribute__((aligned(16))) char smem[73728];
;   cg::grid_group grid = cg::this_grid();
_Z4mega6Params:
	s_load_dwordx4 s[60:63], s[0:1], 0xa0
	s_load_dwordx8 s[52:59], s[0:1], 0x80
	v_writelane_b32 v224, s2, 0
	s_bitcmp1_b32 s2, 0
	s_cbranch_scc0 .Lprio_entry_done
	s_setprio 1
.Lprio_entry_done:
	s_add_u32 s2, s0, 0xa8
	s_addc_u32 s3, s1, 0
	v_writelane_b32 v224, s2, 1
	v_and_b32_e32 v174, 0x3ff, v0
	v_mov_b32_e32 v1, v174
	v_writelane_b32 v224, s3, 2
	s_waitcnt lgkmcnt(0)
	s_add_u32 s2, s60, 0x3df60100
	s_addc_u32 s3, s61, 0
	v_writelane_b32 v224, s2, 3
	s_nop 0
	v_cmp_eq_u32_e32 vcc, 0, v1
	v_writelane_b32 v224, s3, 4
	s_and_saveexec_b64 s[4:5], vcc
	s_cbranch_execz .LBB0_20
	s_load_dword s10, s[0:1], 0xb0
	s_getreg_b32 s6, hwreg(HW_REG_XCC_ID, 0, 4)
	s_mov_b64 s[2:3], exec
	s_and_b32 s24, s6, 15
	s_lshl_b32 s6, s24, 8
	v_readlane_b32 s8, v224, 3
	v_mbcnt_lo_u32_b32 v1, s2, 0
	v_readlane_b32 s9, v224, 4
	s_add_u32 s6, s8, s6
	v_mbcnt_hi_u32_b32 v1, s3, v1
	s_addc_u32 s7, s9, 0
	v_cmp_eq_u32_e32 vcc, 0, v1
	s_and_saveexec_b64 s[8:9], vcc
	s_cbranch_execz .LBB0_3
	s_bcnt1_i32_b64 s2, s[2:3]
	v_mov_b32_e32 v1, 0
	v_mov_b32_e32 v2, s2
	global_atomic_add v1, v2, s[6:7] offset:1024

; __device__ __forceinline__ int ptid() { int t = __builtin_amdgcn_workitem_id_x(); asm volatile("" : "+v"(t)); return t; }
; __device__ __forceinline__ unsigned xb_xcc_id() { return (unsigned)__builtin_amdgcn_s_getreg((3 << 11) | 20) & 0xFu; }
; static __device__ __forceinline__ void phase3(const Params& p, char* smraw) {
;     ...
;   for (int item = blockIdx.x; item < 384; item += gridDim.x) scan_item(p, item, smraw);
;     ...
;   {
;     const int myhead = (int)(xb_xcc_id() & 7u);
;     int* s_item = (int*)(smraw + 65536);
;     for (int hh = 0; hh < 8; ++hh) {
;       const int head = (myhead + hh) & 7;
;       int* cnt = (int*)(p.ws + WS_CNT) + head;
;       for (;;) {
;         if (ptid() == 0) *s_item = atomicAdd(cnt, 1);
;         __syncthreads();
;         const int j = *s_item;
;         __syncthreads();
;         if (j >= 768) break;
;         attn_item(p, head, j, smraw);
;       }
;     }
;   }
.LBB0_386:
	v_readlane_b32 s98, v224, 0
	s_nop 3
	s_bitcmp1_b32 s98, 0
	s_cbranch_scc0 .Lprio_p3_done
	s_setprio 1
